# speedup vs baseline: 1.0115x; 1.0064x over previous
; #define ALAS __attribute__((address_space(3)))
; template <int MODE>
; __device__ __forceinline__ void attn_unit(const UnitP& P, ALAS char* lds, const float* __restrict__ sub_gain, const int wv0, unsigned& hgen, unsigned* qctr, const int xcd) {
;     ...
;     for (int it = 0;; ++it) {
;         const int sl = it & 1;
;         if (t >= 1) ATT_DMA(t - 1, sl ^ 1);
;         if (active && t <= tspec && P.dry < 2) {
;             const ALAS char* kt = ring + sl * SLOT; const ALAS float* kbrow = (const ALAS float*)(lds + L_KB + (hf * NB + sl) * 256);
;             if (t == tspec) {
.LBB0_295:
	s_mov_b32 s11, s13
	s_and_b32 s12, s6, 1
	s_cmp_lt_i32 s11, 1
	s_cbranch_scc1 .LBB0_297
	s_cmp_lt_i32 s11, s8
	s_cselect_b64 s[80:81], -1, 0
	s_and_b64 s[80:81], s[4:5], s[80:81]
	s_and_b64 vcc, exec, s[80:81]
	s_cbranch_vccnz .LBB0_297

; #define ALAS __attribute__((address_space(3)))
; template <int MODE, bool SPECIAL, int KS> ...
;     const int ka0 = r32 * 256 + 16 * (((kcol0 >> 3) + hi) ^ (((r32 & 3) << 2) | ((r32 >> 2) & 3)));
;     int ka0v = ka0; asm volatile("" : "+v"(ka0v));
;     const float U = MODE == 1 ? P.cref : (SPECIAL ? 0.f : P.slope2 * (float)(64 * t + 4 * hi - P.qpos0));
;     f32x16 s[2];
; #pragma unroll
;     for (int blk = 0; blk < 2; ++blk)
; #pragma unroll
;         for (int r = 0; r < 16; ++r) s[blk][r] = 0.f;
; #pragma unroll
;     for (int ks = 0; ks < KS; ++ks)
; #pragma unroll
;         for (int blk = 0; blk < 2; ++blk) {
;             const bf16x8 kf = *(const ALAS bf16x8*)(kt + (ka0v ^ (32 * ks)) + 8192 * blk);
;     ...
;     const int vq = (lane & 15) >> 2, vp = lane & 3;
;     const int vb0 = 8 * (vp & 1) + 16 * ((vp >> 1) ^ hi) + 32 * ((lane >> 4) & 1) + 320 * vq + 1024 * hi;
;     int vb0v = vb0; asm volatile("" : "+v"(vb0v));
.LBB0_297:
	s_cmp_le_i32 s11, s8
	s_cselect_b64 s[80:81], -1, 0
	s_and_b64 s[80:81], s[4:5], s[80:81]
	s_andn2_b64 vcc, exec, s[80:81]
	s_cbranch_vccnz .LBB0_307
	s_lshl_b32 s13, s12, 15
	s_add_i32 s13, s91, s13
	s_cmp_lg_u32 s11, s8
	s_mov_b64 s[80:81], -1
	s_cbranch_scc0 .LBB0_302
	v_add_u32_e32 v108, s13, v180
	v_xad_u32 v109, v180, 32, s13
	v_xad_u32 v110, v180, 64, s13
	v_xor_b32_e32 v111, 0x60, v180
	ds_read_b128 v[68:71], v108
	ds_read_b128 v[72:75], v108 offset:8192
	v_add_u32_e32 v111, s13, v111
	ds_read_b128 v[76:79], v109
	ds_read_b128 v[80:83], v110
	ds_read_b128 v[84:87], v109 offset:8192
	ds_read_b128 v[88:91], v111
	ds_read_b128 v[92:95], v110 offset:8192
	ds_read_b128 v[96:99], v111 offset:8192
	v_add_u32_e32 v100, s13, v181
	v_xad_u32 v101, v181, 64, s13
	v_xor_b32_e32 v102, 0x80, v181
	v_xor_b32_e32 v103, 0xc0, v181
	v_xor_b32_e32 v104, 0x820, v181
	v_xor_b32_e32 v105, 0x860, v181
	v_xor_b32_e32 v106, 0x8a0, v181
	v_xor_b32_e32 v107, 0x8e0, v181
	v_add_u32_e32 v102, s13, v102
	v_add_u32_e32 v103, s13, v103
	v_add_u32_e32 v104, s13, v104
	v_add_u32_e32 v105, s13, v105
	v_add_u32_e32 v106, s13, v106
	v_add_u32_e32 v107, s13, v107

; __device__ __forceinline__ float max32(float v) { auto rr = __builtin_amdgcn_permlane32_swap(__float_as_uint(v), __float_as_uint(v), false, false); return fmaxf(__uint_as_float(rr[0]), __uint_as_float(rr[1])); }
; #define ALAS __attribute__((address_space(3)))
; template <int MODE, bool SPECIAL, int KS> ...
;     ...
;     for (int ks = 0; ks < KS; ++ks)
; #pragma unroll
;         for (int blk = 0; blk < 2; ++blk) {
;             const bf16x8 kf = *(const ALAS bf16x8*)(kt + (ka0v ^ (32 * ks)) + 8192 * blk);
;             s[blk] = __builtin_amdgcn_mfma_f32_32x32x16_bf16(kf, qf[ks], s[blk], 0, 0, 0);
;         }
;     const ALAS float* kbp = kbrow + 4 * hi;
;     if constexpr (!SPECIAL) {
;         if constexpr (MODE == 0) {
; #pragma unroll
;             for (int blk = 0; blk < 2; ++blk)
; #pragma unroll
;                 for (int r = 0; r < 16; ++r) s[blk][r] = __builtin_fmaf((float)(32 * blk + (r & 3) + 8 * (r >> 2)), P.slope2, s[blk][r]);
;         } else {
; #pragma unroll
;             for (int blk = 0; blk < 2; ++blk)
; #pragma unroll
;                 for (int g = 0; g < 4; ++g) { const f32x4 kv = *(const ALAS f32x4*)(kbp + 32 * blk + 8 * g);
; #pragma unroll
;                     for (int e = 0; e < 4; ++e) s[blk][4 * g + e] -= kv[e]; }
;         }
;     } else {
;         const int qpos = P.qpos0 + qw0 + r32;
; #pragma unroll
;         for (int blk = 0; blk < 2; ++blk)
; #pragma unroll
;             for (int g = 0; g < 4; ++g) {
;                 f32x4 kv = (f32x4){0.f, 0.f, 0.f, 0.f};
;                 if constexpr (MODE == 1) kv = *(const ALAS f32x4*)(kbp + 32 * blk + 8 * g);
; #pragma unroll
;                 for (int e = 0; e < 4; ++e) {
;                     const int kpos = 64 * t + 32 * blk + 8 * g + 4 * hi + e;
;                     float b; bool ok;
;                     if constexpr (MODE == 0) { const int mn = min(kpos, 2 * qpos - kpos); b = P.slope2 * (float)(mn - P.qpos0); ok = kpos < P.nkeys; }
;                     else { b = -kv[e]; ok = kpos <= qpos; }
;                     const float x = s[blk][4 * g + e] + b;
;                     s[blk][4 * g + e] = ok ? x : -INFINITY;
;                 }
;             }
;     }
;     float mx = s[0][0];
; #pragma unroll
;     for (int r = 1; r < 16; ++r) mx = fmaxf(mx, s[0][r]);
; #pragma unroll
;     for (int r = 0; r < 16; ++r) mx = fmaxf(mx, s[1][r]);
;     mx += U;
;     mx = max32(mx);
	s_cmp_lg_u32 s11, 0
	s_cbranch_scc0 .Ltd_0
	s_add_i32 s82, s11, -1
	s_mul_hi_u32 s81, s82, s94
	s_mul_i32 s80, s82, s94
	s_lshl_b32 s82, s12, 15
	s_xor_b32 s82, s82, 0x8000
	s_lshl_b64 s[80:81], s[80:81], 7
	s_add_i32 s82, s33, s82
	v_lshl_add_u64 v[240:241], v[164:165], 0, s[80:81]
	v_lshl_add_u64 v[242:243], v[166:167], 0, s[80:81]
	v_lshl_add_u64 v[246:247], v[240:241], 0, v[176:177]
	s_mov_b32 m0, s82
	v_lshl_add_u64 v[240:241], v[240:241], 0, s[2:3]
	global_load_lds_dwordx4 v[246:247], off
	v_lshl_add_u64 v[246:247], v[242:243], 0, v[176:177]
	s_add_i32 m0, s82, 0x4000
	v_lshl_add_u64 v[242:243], v[242:243], 0, s[2:3]
	global_load_lds_dwordx4 v[246:247], off
.Ltd_0:
	v_mov_b32_e32 v169, v203
	s_waitcnt lgkmcnt(7)
	v_mfma_f32_32x32x16_bf16 v[130:145], v[68:71], v[146:149], 0
	s_waitcnt lgkmcnt(6)
	v_mfma_f32_32x32x16_bf16 v[114:129], v[72:75], v[146:149], 0
	s_waitcnt lgkmcnt(5)
	v_mfma_f32_32x32x16_bf16 v[130:145], v[76:79], v[150:153], v[130:145]
	s_waitcnt lgkmcnt(4)
	v_mfma_f32_32x32x16_bf16 v[130:145], v[80:83], v[154:157], v[130:145]
	s_cmp_lg_u32 s11, 0
	s_cbranch_scc0 .Ltd_1
	v_mov_b32_e32 v244, v168
	v_mov_b32_e32 v245, v177
	v_lshl_add_u64 v[246:247], v[240:241], 0, v[244:245]
	s_add_i32 m0, s82, 0x400
	v_lshl_add_u64 v[240:241], v[240:241], 0, s[96:97]
	global_load_lds_dwordx4 v[246:247], off
	v_lshl_add_u64 v[246:247], v[242:243], 0, v[244:245]
	s_add_i32 m0, s82, 0x4400
	v_lshl_add_u64 v[242:243], v[242:243], 0, s[96:97]
	global_load_lds_dwordx4 v[246:247], off
.Ltd_1:
	s_waitcnt lgkmcnt(3)
	v_mfma_f32_32x32x16_bf16 v[114:129], v[84:87], v[150:153], v[114:129]
	s_waitcnt lgkmcnt(2)
	v_mfma_f32_32x32x16_bf16 v[130:145], v[88:91], v[158:161], v[130:145]
	v_lshl_add_u32 v64, s11, 6, v182
	v_cvt_f32_i32_e32 v236, v64
	s_waitcnt lgkmcnt(1)
	v_mfma_f32_32x32x16_bf16 v[114:129], v[92:95], v[154:157], v[114:129]
	s_waitcnt lgkmcnt(0)
	s_nop 8
	v_fma_f32 v237, 0, v179, v130
	v_add_f32_e32 v235, v179, v131
	v_fma_f32 v234, 2.0, v179, v132
	v_fmamk_f32 v233, v179, 0x40400000, v133
	v_max_f32_e32 v64, v237, v235
	v_fmamk_f32 v232, v179, 0x41000000, v134
	v_fmamk_f32 v231, v179, 0x41100000, v135
	v_mfma_f32_32x32x16_bf16 v[114:129], v[96:99], v[158:161], v[114:129]
	v_max3_f32 v64, v64, v234, v233
	v_fmamk_f32 v230, v179, 0x41200000, v136
	v_fmamk_f32 v229, v179, 0x41300000, v137
	ds_read_b64_tr_b16 v[68:69], v100 offset:16384
	ds_read_b64_tr_b16 v[70:71], v104 offset:16384
	v_max3_f32 v64, v64, v232, v231
	v_fmamk_f32 v228, v179, 0x41800000, v138
	v_fmamk_f32 v227, v179, 0x41880000, v139
	ds_read_b64_tr_b16 v[72:73], v101 offset:16384
	ds_read_b64_tr_b16 v[74:75], v105 offset:16384
	v_max3_f32 v64, v64, v230, v229
	v_fmamk_f32 v226, v179, 0x41900000, v140
	v_fmamk_f32 v225, v179, 0x41980000, v141
	ds_read_b64_tr_b16 v[76:77], v102 offset:16384
	ds_read_b64_tr_b16 v[78:79], v106 offset:16384
	v_max3_f32 v64, v64, v228, v227
	v_fmamk_f32 v224, v179, 0x41c00000, v142
	v_fmamk_f32 v173, v179, 0x41c80000, v143
	ds_read_b64_tr_b16 v[80:81], v103 offset:16384
	ds_read_b64_tr_b16 v[82:83], v107 offset:16384
	v_max3_f32 v64, v64, v226, v225
	v_fmamk_f32 v171, v179, 0x41d00000, v144
	v_fmac_f32_e32 v145, 0x41d80000, v179
	ds_read_b64_tr_b16 v[84:85], v100 offset:20480
	ds_read_b64_tr_b16 v[86:87], v104 offset:20480
	v_max3_f32 v64, v64, v224, v173
	v_fmamk_f32 v144, v179, 0x42000000, v114
	v_fmamk_f32 v143, v179, 0x42040000, v115
	ds_read_b64_tr_b16 v[88:89], v101 offset:20480
	ds_read_b64_tr_b16 v[90:91], v105 offset:20480
	v_max3_f32 v64, v64, v171, v145
	v_fmamk_f32 v142, v179, 0x42080000, v116
	v_fmamk_f32 v141, v179, 0x420c0000, v117
	v_max3_f32 v64, v64, v144, v143
	v_fmamk_f32 v140, v179, 0x42200000, v118
	v_fmamk_f32 v139, v179, 0x42240000, v119
	s_cmp_lg_u32 s11, 0
	s_cbranch_scc0 .Ltd_2
	v_mov_b32_e32 v244, v170
	v_mov_b32_e32 v245, v177
	v_lshl_add_u64 v[246:247], v[240:241], 0, v[244:245]
	s_add_i32 m0, s82, 0x800
	v_lshl_add_u64 v[240:241], v[240:241], 0, s[96:97]
	global_load_lds_dwordx4 v[246:247], off
	v_lshl_add_u64 v[246:247], v[242:243], 0, v[244:245]
	s_add_i32 m0, s82, 0x4800
	v_lshl_add_u64 v[242:243], v[242:243], 0, s[96:97]
	global_load_lds_dwordx4 v[246:247], off
.Ltd_2:
	v_max3_f32 v64, v64, v142, v141
	v_fmamk_f32 v138, v179, 0x42280000, v120
	v_fmamk_f32 v136, v179, 0x422c0000, v121
	v_max3_f32 v64, v64, v140, v139
	v_fmamk_f32 v135, v179, 0x42400000, v122
	v_fmamk_f32 v134, v179, 0x42440000, v123
	v_max3_f32 v64, v64, v138, v136
	v_fmamk_f32 v133, v179, 0x42480000, v124
	v_fmamk_f32 v132, v179, 0x424c0000, v125
	v_max3_f32 v64, v64, v135, v134
	v_fmamk_f32 v131, v179, 0x42600000, v126
	v_fmamk_f32 v130, v179, 0x42640000, v127
	v_max3_f32 v64, v64, v133, v132
	v_fmamk_f32 v128, v179, 0x42680000, v128
	v_fmac_f32_e32 v129, 0x426c0000, v179
	v_max3_f32 v64, v64, v131, v130
	v_max3_f32 v64, v64, v128, v129
	v_fmac_f32_e32 v64, v179, v236
	v_mov_b32_e32 v65, v64
	s_nop 1
	v_permlane32_swap_b32_e32 v64, v65
	v_max_f32_e32 v65, v65, v65
	v_max_f32_e32 v64, v64, v64
	v_max_f32_e32 v238, v64, v65
	v_add_f32_e32 v64, 0x41a00000, v203
	v_cmp_gt_f32_e32 vcc, v238, v64
	v_mov_b32_e32 v137, v222
	s_cbranch_vccz .LBB0_301
; template <int MODE, bool SPECIAL, int KS> ...
;     ...
;     if (__any(mx > mrun + 20.f)) {
;         const float mnew = fmaxf(mrun, mx);
;         const float alpha = __builtin_amdgcn_exp2f(mrun - mnew);
;         mrun = mnew; lsum *= alpha;
; #pragma unroll
;         for (int d0 = 0; d0 < 4; ++d0)
; #pragma unroll
;             for (int r = 0; r < 16; ++r) o[d0][r] *= alpha;
;     }
;     const float sub = mrun - U;
	v_max_f32_e32 v64, v238, v238
	v_max_f32_e32 v65, v203, v203
	v_max_f32_e32 v169, v65, v64
	v_sub_f32_e32 v64, v203, v169
	v_exp_f32_e32 v112, v64
	s_nop 0
	v_mul_f32_e32 v137, v222, v112
	v_pk_mul_f32 v[62:63], v[62:63], v[112:113] op_sel_hi:[1,0]
	v_pk_mul_f32 v[60:61], v[60:61], v[112:113] op_sel_hi:[1,0]
	v_pk_mul_f32 v[58:59], v[58:59], v[112:113] op_sel_hi:[1,0]
	v_pk_mul_f32 v[56:57], v[56:57], v[112:113] op_sel_hi:[1,0]
	v_pk_mul_f32 v[54:55], v[54:55], v[112:113] op_sel_hi:[1,0]
	v_pk_mul_f32 v[52:53], v[52:53], v[112:113] op_sel_hi:[1,0]
	v_pk_mul_f32 v[50:51], v[50:51], v[112:113] op_sel_hi:[1,0]
	v_pk_mul_f32 v[48:49], v[48:49], v[112:113] op_sel_hi:[1,0]
	v_pk_mul_f32 v[46:47], v[46:47], v[112:113] op_sel_hi:[1,0]
	v_pk_mul_f32 v[44:45], v[44:45], v[112:113] op_sel_hi:[1,0]
	v_pk_mul_f32 v[42:43], v[42:43], v[112:113] op_sel_hi:[1,0]
	v_pk_mul_f32 v[40:41], v[40:41], v[112:113] op_sel_hi:[1,0]
	v_pk_mul_f32 v[38:39], v[38:39], v[112:113] op_sel_hi:[1,0]
	v_pk_mul_f32 v[36:37], v[36:37], v[112:113] op_sel_hi:[1,0]
	v_pk_mul_f32 v[34:35], v[34:35], v[112:113] op_sel_hi:[1,0]
	v_pk_mul_f32 v[32:33], v[32:33], v[112:113] op_sel_hi:[1,0]
	v_pk_mul_f32 v[30:31], v[30:31], v[112:113] op_sel_hi:[1,0]
	v_pk_mul_f32 v[28:29], v[28:29], v[112:113] op_sel_hi:[1,0]
	v_pk_mul_f32 v[26:27], v[26:27], v[112:113] op_sel_hi:[1,0]
	v_pk_mul_f32 v[24:25], v[24:25], v[112:113] op_sel_hi:[1,0]
	v_pk_mul_f32 v[22:23], v[22:23], v[112:113] op_sel_hi:[1,0]
	v_pk_mul_f32 v[20:21], v[20:21], v[112:113] op_sel_hi:[1,0]
	v_pk_mul_f32 v[18:19], v[18:19], v[112:113] op_sel_hi:[1,0]
	v_pk_mul_f32 v[16:17], v[16:17], v[112:113] op_sel_hi:[1,0]
	v_pk_mul_f32 v[14:15], v[14:15], v[112:113] op_sel_hi:[1,0]
	v_pk_mul_f32 v[12:13], v[12:13], v[112:113] op_sel_hi:[1,0]
	v_pk_mul_f32 v[10:11], v[10:11], v[112:113] op_sel_hi:[1,0]
	v_pk_mul_f32 v[8:9], v[8:9], v[112:113] op_sel_hi:[1,0]
	v_pk_mul_f32 v[6:7], v[6:7], v[112:113] op_sel_hi:[1,0]
	v_pk_mul_f32 v[4:5], v[4:5], v[112:113] op_sel_hi:[1,0]
	v_pk_mul_f32 v[2:3], v[2:3], v[112:113] op_sel_hi:[1,0]
	v_pk_mul_f32 v[0:1], v[0:1], v[112:113] op_sel_hi:[1,0]
.LBB0_301:
	v_mul_f32_e32 v236, v179, v236
	v_sub_f32_e32 v236, v169, v236
	s_cmp_lg_u32 s11, 0
	s_cbranch_scc0 .Ltd_3
	v_mov_b32_e32 v244, v172
	v_mov_b32_e32 v245, v177
	v_lshl_add_u64 v[246:247], v[240:241], 0, v[244:245]
	s_add_i32 m0, s82, 0xc00
	s_nop 0
	global_load_lds_dwordx4 v[246:247], off
	v_lshl_add_u64 v[246:247], v[242:243], 0, v[244:245]
	s_add_i32 m0, s82, 0x4c00
	s_nop 0
	global_load_lds_dwordx4 v[246:247], off
; __device__ __forceinline__ unsigned cvtpk(float lo, float hi) { f32x2 v = {lo, hi}; bf16x2_t b = __builtin_convertvector(v, bf16x2_t); return __builtin_bit_cast(unsigned, b); }
; __device__ __forceinline__ s16x4 vtr(const ALAS char* p) { return __builtin_bit_cast(s16x4, __builtin_amdgcn_ds_read_tr16_b64_v4i16((ALAS v4i16_t*)p)); }
; template <int MODE, bool SPECIAL, int KS> ...
;     ...
;     const float sub = mrun - U;
;     float rs = 0.f;
; #pragma unroll
;     for (int blk = 0; blk < 2; ++blk)
; #pragma unroll
;         for (int r = 0; r < 16; ++r) { const float p = __builtin_amdgcn_exp2f(s[blk][r] - sub); s[blk][r] = p; rs += p; }
;     lsum += rs;
;     bf16x8 pf[4];
; #pragma unroll
;     for (int kk = 0; kk < 4; ++kk) {
;         const int blk = kk >> 1, b8 = 8 * (kk & 1);
;         u32x4 w; w.x = cvtpk(s[blk][b8 + 0], s[blk][b8 + 1]); w.y = cvtpk(s[blk][b8 + 2], s[blk][b8 + 3]);
;         w.z = cvtpk(s[blk][b8 + 4], s[blk][b8 + 5]); w.w = cvtpk(s[blk][b8 + 6], s[blk][b8 + 7]);
;         pf[kk] = __builtin_bit_cast(bf16x8, w);
;     }
;     const int vq = (lane & 15) >> 2, vp = lane & 3;
;     const int vb0 = 8 * (vp & 1) + 16 * ((vp >> 1) ^ hi) + 32 * ((lane >> 4) & 1) + 320 * vq + 1024 * hi;
;     int vb0v = vb0; asm volatile("" : "+v"(vb0v));
; #pragma unroll
;     for (int d0 = 0; d0 < 4; ++d0) {
; #pragma unroll
;         for (int kk = 0; kk < 4; ++kk) {
;             const s16x4 lo = vtr(kt + 16384 + (vb0v ^ (64 * d0)) + 4096 * kk), hh = vtr(kt + 16384 + ((vb0v ^ (64 * d0)) ^ 2080) + 4096 * kk);
;             const bf16x8 vf = (bf16x8){lo[0], lo[1], lo[2], lo[3], hh[0], hh[1], hh[2], hh[3]};
;             o[d0] = __builtin_amdgcn_mfma_f32_32x32x16_bf16(vf, pf[kk], o[d0], 0, 0, 0);
;         }
;     }
.Ltd_3:
	v_sub_f32_e32 v237, v237, v236
	v_sub_f32_e32 v235, v235, v236
	v_exp_f32_e32 v237, v237
	v_sub_f32_e32 v234, v234, v236
	v_exp_f32_e32 v235, v235
	v_sub_f32_e32 v233, v233, v236
	v_exp_f32_e32 v234, v234
	v_add_f32_e32 v238, 0, v237
	v_sub_f32_e32 v232, v232, v236
	v_exp_f32_e32 v233, v233
	v_add_f32_e32 v238, v235, v238
	v_sub_f32_e32 v231, v231, v236
	v_exp_f32_e32 v232, v232
	v_add_f32_e32 v238, v234, v238
	v_sub_f32_e32 v230, v230, v236
	v_exp_f32_e32 v231, v231
	v_add_f32_e32 v238, v233, v238
	v_sub_f32_e32 v229, v229, v236
	v_exp_f32_e32 v230, v230
	v_add_f32_e32 v238, v232, v238
	v_exp_f32_e32 v229, v229
	v_add_f32_e32 v238, v231, v238
	v_add_f32_e32 v238, v230, v238
	v_cvt_pk_bf16_f32 v92, v237, v235
	v_cvt_pk_bf16_f32 v93, v234, v233
	v_cvt_pk_bf16_f32 v94, v232, v231
	v_cvt_pk_bf16_f32 v95, v230, v229
	v_add_f32_e32 v238, v229, v238
	s_nop 0
	s_waitcnt lgkmcnt(10)
	v_mfma_f32_32x32x16_bf16 v[48:63], v[68:71], v[92:95], v[48:63]
	ds_read_b64_tr_b16 v[68:69], v102 offset:20480
	ds_read_b64_tr_b16 v[70:71], v106 offset:20480
	v_sub_f32_e32 v228, v228, v236
	v_sub_f32_e32 v227, v227, v236
	v_exp_f32_e32 v228, v228
	v_sub_f32_e32 v226, v226, v236
	v_exp_f32_e32 v227, v227
	v_sub_f32_e32 v225, v225, v236
	v_exp_f32_e32 v226, v226
	v_add_f32_e32 v238, v228, v238
	s_waitcnt lgkmcnt(10)
	v_mfma_f32_32x32x16_bf16 v[32:47], v[72:75], v[92:95], v[32:47]
	ds_read_b64_tr_b16 v[72:73], v103 offset:20480
	ds_read_b64_tr_b16 v[74:75], v107 offset:20480
	v_sub_f32_e32 v224, v224, v236
	v_exp_f32_e32 v225, v225
	v_add_f32_e32 v238, v227, v238
	v_sub_f32_e32 v173, v173, v236
	v_exp_f32_e32 v224, v224
	v_add_f32_e32 v238, v226, v238
	v_sub_f32_e32 v171, v171, v236
	v_exp_f32_e32 v173, v173
	s_waitcnt lgkmcnt(10)
	v_mfma_f32_32x32x16_bf16 v[16:31], v[76:79], v[92:95], v[16:31]
	ds_read_b64_tr_b16 v[76:77], v100 offset:24576
	ds_read_b64_tr_b16 v[78:79], v104 offset:24576
	v_add_f32_e32 v238, v225, v238
	v_sub_f32_e32 v145, v145, v236
	v_exp_f32_e32 v171, v171
	v_add_f32_e32 v238, v224, v238
	v_exp_f32_e32 v145, v145
	v_add_f32_e32 v238, v173, v238
	v_add_f32_e32 v238, v171, v238
	v_cvt_pk_bf16_f32 v96, v228, v227
	s_waitcnt lgkmcnt(10)
	v_mfma_f32_32x32x16_bf16 v[0:15], v[80:83], v[92:95], v[0:15]
	ds_read_b64_tr_b16 v[80:81], v101 offset:24576
	ds_read_b64_tr_b16 v[82:83], v105 offset:24576
	v_cvt_pk_bf16_f32 v97, v226, v225
	v_cvt_pk_bf16_f32 v98, v224, v173
	v_cvt_pk_bf16_f32 v99, v171, v145
	v_add_f32_e32 v238, v145, v238
	s_nop 0
	s_waitcnt lgkmcnt(10)
	v_mfma_f32_32x32x16_bf16 v[48:63], v[84:87], v[96:99], v[48:63]
	ds_read_b64_tr_b16 v[84:85], v102 offset:24576
	ds_read_b64_tr_b16 v[86:87], v106 offset:24576
	v_sub_f32_e32 v144, v144, v236
	v_sub_f32_e32 v143, v143, v236
	v_exp_f32_e32 v144, v144
	v_sub_f32_e32 v142, v142, v236
	v_exp_f32_e32 v143, v143
	v_sub_f32_e32 v141, v141, v236
	v_exp_f32_e32 v142, v142
	v_add_f32_e32 v238, v144, v238
	s_waitcnt lgkmcnt(10)
	v_mfma_f32_32x32x16_bf16 v[32:47], v[88:91], v[96:99], v[32:47]
	ds_read_b64_tr_b16 v[88:89], v103 offset:24576
	ds_read_b64_tr_b16 v[90:91], v107 offset:24576
	v_sub_f32_e32 v140, v140, v236
	v_exp_f32_e32 v141, v141
	v_add_f32_e32 v238, v143, v238
	v_sub_f32_e32 v139, v139, v236
	v_exp_f32_e32 v140, v140
	v_add_f32_e32 v238, v142, v238
	v_sub_f32_e32 v138, v138, v236
	v_exp_f32_e32 v139, v139
	s_waitcnt lgkmcnt(10)
	v_mfma_f32_32x32x16_bf16 v[16:31], v[68:71], v[96:99], v[16:31]
	ds_read_b64_tr_b16 v[68:69], v100 offset:28672
	ds_read_b64_tr_b16 v[70:71], v104 offset:28672
	v_add_f32_e32 v238, v141, v238
	v_sub_f32_e32 v136, v136, v236
	v_exp_f32_e32 v138, v138
	v_add_f32_e32 v238, v140, v238
	v_exp_f32_e32 v136, v136
	v_add_f32_e32 v238, v139, v238
	v_add_f32_e32 v238, v138, v238
	v_cvt_pk_bf16_f32 v224, v144, v143
	s_waitcnt lgkmcnt(10)
	v_mfma_f32_32x32x16_bf16 v[0:15], v[72:75], v[96:99], v[0:15]
	ds_read_b64_tr_b16 v[72:73], v101 offset:28672
	ds_read_b64_tr_b16 v[74:75], v105 offset:28672
	v_cvt_pk_bf16_f32 v225, v142, v141
	v_cvt_pk_bf16_f32 v226, v140, v139
	v_cvt_pk_bf16_f32 v227, v138, v136
	v_add_f32_e32 v238, v136, v238
	s_nop 0
	s_waitcnt lgkmcnt(10)
	v_mfma_f32_32x32x16_bf16 v[48:63], v[76:79], v[224:227], v[48:63]
	ds_read_b64_tr_b16 v[76:77], v102 offset:28672
	ds_read_b64_tr_b16 v[78:79], v106 offset:28672
	v_sub_f32_e32 v135, v135, v236
	v_sub_f32_e32 v134, v134, v236
	v_exp_f32_e32 v135, v135
	v_sub_f32_e32 v133, v133, v236
	v_exp_f32_e32 v134, v134
	v_sub_f32_e32 v132, v132, v236
	v_exp_f32_e32 v133, v133
	v_add_f32_e32 v238, v135, v238
	s_waitcnt lgkmcnt(10)
	v_mfma_f32_32x32x16_bf16 v[32:47], v[80:83], v[224:227], v[32:47]
	ds_read_b64_tr_b16 v[80:81], v103 offset:28672
	ds_read_b64_tr_b16 v[82:83], v107 offset:28672
	v_sub_f32_e32 v131, v131, v236
	v_exp_f32_e32 v132, v132
	v_add_f32_e32 v238, v134, v238
	v_sub_f32_e32 v130, v130, v236
	v_exp_f32_e32 v131, v131
	v_add_f32_e32 v238, v133, v238
	v_sub_f32_e32 v128, v128, v236
	v_exp_f32_e32 v130, v130
	s_waitcnt lgkmcnt(10)
	v_mfma_f32_32x32x16_bf16 v[16:31], v[84:87], v[224:227], v[16:31]
	v_add_f32_e32 v238, v132, v238
	v_sub_f32_e32 v129, v129, v236
	v_exp_f32_e32 v128, v128
	v_add_f32_e32 v238, v131, v238
	v_exp_f32_e32 v129, v129
	v_add_f32_e32 v238, v130, v238
	v_add_f32_e32 v238, v128, v238
	v_cvt_pk_bf16_f32 v228, v135, v134
	s_waitcnt lgkmcnt(8)
	v_mfma_f32_32x32x16_bf16 v[0:15], v[88:91], v[224:227], v[0:15]
	v_cvt_pk_bf16_f32 v229, v133, v132
	v_cvt_pk_bf16_f32 v230, v131, v130
	v_cvt_pk_bf16_f32 v231, v128, v129
	v_add_f32_e32 v238, v129, v238
	s_nop 0
	s_waitcnt lgkmcnt(6)
	v_mfma_f32_32x32x16_bf16 v[48:63], v[68:71], v[228:231], v[48:63]
	s_waitcnt lgkmcnt(4)
	v_mfma_f32_32x32x16_bf16 v[32:47], v[72:75], v[228:231], v[32:47]
	s_waitcnt lgkmcnt(2)
	v_mfma_f32_32x32x16_bf16 v[16:31], v[76:79], v[228:231], v[16:31]
	s_waitcnt lgkmcnt(0)
	v_mfma_f32_32x32x16_bf16 v[0:15], v[80:83], v[228:231], v[0:15]
	v_add_f32_e32 v144, v137, v238
	s_mov_b64 s[80:81], 0
